# attention queue: next item popped at the top of the last key tile, collected by the item epilogue wait; no store drain or atomic round trip between items
# speedup vs baseline: 1.0083x; 1.0026x over previous
.LBB0_306:
	s_andn2_b64 vcc, exec, s[2:3]
	s_cbranch_vccnz .LBB0_495
	v_readlane_b32 s2, v251, 42
	v_readlane_b32 s3, v251, 43
	s_lshl_b32 s2, s2, 6
	s_ashr_i32 s3, s2, 31
	s_lshl_b64 s[2:3], s[2:3], 2
	v_readlane_b32 s0, v253, 0
	s_add_u32 s2, s0, s2
	v_readlane_b32 s0, v253, 1
	s_addc_u32 s3, s0, s3
	v_writelane_b32 v251, s2, 49
	s_nop 1
	v_writelane_b32 v251, s3, 50
	v_writelane_b32 v251, s90, 51
	v_mov_b32_e32 v255, -1
	s_branch .LBB0_312

.LBB0_312:
	s_mov_b64 s[2:3], exec
	v_readlane_b32 s4, v253, 50
	v_readlane_b32 s5, v253, 51
	s_and_b64 s[4:5], s[2:3], s[4:5]
	s_waitcnt lgkmcnt(0)
	s_mov_b64 exec, s[4:5]
	s_cbranch_execz .Lpop_have
	v_cmp_ne_u32_e32 vcc, -1, v255
	s_cbranch_vccnz .Lpop_have
	v_readlane_b32 s6, v251, 49
	v_readlane_b32 s7, v251, 50
	v_mov_b32_e32 v255, 1
	s_nop 3
	global_atomic_add v255, v3, v255, s[6:7] sc0
	s_waitcnt vmcnt(0)
.Lpop_have:
	s_mov_b64 exec, s[2:3]
	s_barrier
	s_mov_b64 exec, s[4:5]
	s_cbranch_execz .LBB0_316
	ds_write_b32 v188, v255
	s_nop 1
	v_mov_b32_e32 v255, -1

.LBB0_374:
	s_cmp_lg_u32 s26, 1
	s_cbranch_scc0 .LBB0_376
	s_waitcnt vmcnt(0)
	v_readlane_b32 s98, v253, 50
	v_readlane_b32 s99, v253, 51
	v_readlane_b32 s100, v251, 49
	v_readlane_b32 s101, v251, 50
	s_nop 0
	s_mov_b64 exec, s[98:99]
	s_cbranch_execz .Lep96_skip
	v_mov_b32_e32 v255, 1
	s_nop 1
	global_atomic_add v255, v3, v255, s[100:101] sc0
.Lep96_skip:
	s_mov_b64 exec, -1
	s_mov_b64 s[2:3], 0

.LBB0_405:
	s_cmp_lt_i32 s41, 2
	s_mov_b64 s[36:37], -1
	s_cbranch_scc0 .LBB0_411
	s_cmp_lg_u32 s41, 1
	s_cbranch_scc0 .LBB0_408
	s_waitcnt vmcnt(0)
	v_readlane_b32 s98, v253, 50
	v_readlane_b32 s99, v253, 51
	v_readlane_b32 s100, v251, 49
	v_readlane_b32 s101, v251, 50
	s_nop 0
	s_mov_b64 exec, s[98:99]
	s_cbranch_execz .Lep64_skip
	v_mov_b32_e32 v255, 1
	s_nop 1
	global_atomic_add v255, v3, v255, s[100:101] sc0
.Lep64_skip:
	s_mov_b64 exec, -1
	s_mov_b64 s[36:37], 0
